# fox fast path with rescale threshold T=40 (lazy rescale), prefetch, scan deserialize
# speedup vs baseline: 1.0527x; 1.0527x over previous
; DI float ex2(float x) { return __builtin_amdgcn_exp2f(x); }
; DI f32x4 mmaT(bf16x8 a_m, bf16x8 b_n, f32x4 c) { return __builtin_amdgcn_mfma_f32_16x16x32_bf16(b_n, a_m, c, 0, 0, 0); }
; DI v4i16_t tr_rd(const bf16_t* a) { return __builtin_amdgcn_ds_read_tr16_b64_v4i16((LDSP v4i16_t*)a); }
; DI float shx(float v, int m, int lane) { return __int_as_float(__builtin_amdgcn_ds_bpermute((lane ^ m) << 2, __float_as_int(v))); }
; template <bool DIAG>
; DI void fox_tile(const bf16_t* sK, const bf16_t* sV, const float* sFk, const bf16x8 (&qf)[2][2], f32x4 (&o)[2][4], float (&mrun)[2], float (&lsum)[2], int key0, int qg0, int fr, int fq, int lane) {
;   const float SC2 = 0.125f * LOG2E;
;   f32x4 s[2][4];
;   const int kof = (fr * 64 + fq * 16) ^ ((fr >> 3) << 5);
; #pragma unroll
;   for (int t = 0; t < 4; ++t) {
;     const bf16x8 k0 = *(const bf16x8*)((const unsigned char*)sK + (t * 2) * 1024 + kof), k1 = *(const bf16x8*)((const unsigned char*)sK + (t * 2 + 1) * 1024 + kof);
; #pragma unroll
;     for (int mi = 0; mi < 2; ++mi) { s[mi][t] = mmaT(qf[mi][0], k0, (f32x4){0.f, 0.f, 0.f, 0.f}); s[mi][t] = mmaT(qf[mi][1], k1, s[mi][t]); }
;   }
;   f32x4 fk[4];
; #pragma unroll
;   for (int t = 0; t < 4; ++t) fk[t] = *(const f32x4*)(sFk + 16 * t + 4 * fq);
;   __builtin_amdgcn_sched_barrier(0);
;   bf16x8 vf[2][4];
; #pragma unroll
;   for (int k2 = 0; k2 < 2; ++k2)
; #pragma unroll
;     for (int d = 0; d < 4; ++d) {
;       const bf16_t* a = sV + (32 * k2 + 4 * fq + (fr >> 2)) * 72 + 16 * d + 4 * (fr & 3);
;       const v4i16_t lo = tr_rd(a), hi = tr_rd(a + 16 * 72);
;       vf[k2][d] = __builtin_shufflevector(lo, hi, 0, 1, 2, 3, 4, 5, 6, 7);
;     }
;   __builtin_amdgcn_sched_barrier(0);
; #pragma unroll
;   for (int mi = 0; mi < 2; ++mi) {
;     float mx = -INFINITY;
; #pragma unroll
;     for (int t = 0; t < 4; ++t)
; #pragma unroll
;       for (int j = 0; j < 4; ++j) {
;         float x = __builtin_fmaf(s[mi][t][j], SC2, fk[t][j]);
;         if (DIAG) { if (key0 + 16 * t + 4 * fq + j > qg0 + 16 * mi) x = -INFINITY; }
;         s[mi][t][j] = x; mx = fmaxf(mx, x);
;       }
;     mx = fmaxf(mx, shx(mx, 16, lane)); mx = fmaxf(mx, shx(mx, 32, lane));
;     const float mnew = fmaxf(mrun[mi], mx), alpha = ex2(mrun[mi] - mnew);
.LBB0_491:
	s_andn2_b64 vcc, exec, s[4:5]
	s_cbranch_vccnz .LBB0_493
	s_waitcnt lgkmcnt(11)
	v_mfma_f32_16x16x32_bf16 v[72:75], v[64:67], v[0:3], v[224:227]
	v_mfma_f32_16x16x32_bf16 v[84:87], v[64:67], v[8:11], v[228:231]
	s_waitcnt lgkmcnt(10)
	v_mfma_f32_16x16x32_bf16 v[72:75], v[68:71], v[4:7], v[72:75]
	v_mfma_f32_16x16x32_bf16 v[84:87], v[68:71], v[12:15], v[84:87]
	s_waitcnt lgkmcnt(9)
	v_mfma_f32_16x16x32_bf16 v[76:79], v[56:59], v[0:3], v[224:227]
	v_mfma_f32_16x16x32_bf16 v[88:91], v[56:59], v[8:11], v[228:231]
	s_waitcnt lgkmcnt(8)
	v_mfma_f32_16x16x32_bf16 v[76:79], v[60:63], v[4:7], v[76:79]
	v_mfma_f32_16x16x32_bf16 v[88:91], v[60:63], v[12:15], v[88:91]
	s_waitcnt lgkmcnt(7)
	v_mfma_f32_16x16x32_bf16 v[80:83], v[48:51], v[0:3], v[224:227]
	v_mfma_f32_16x16x32_bf16 v[92:95], v[48:51], v[8:11], v[228:231]
	s_waitcnt lgkmcnt(6)
	v_mfma_f32_16x16x32_bf16 v[80:83], v[52:55], v[4:7], v[80:83]
	v_mfma_f32_16x16x32_bf16 v[92:95], v[52:55], v[12:15], v[92:95]
	s_waitcnt lgkmcnt(5)
	v_mfma_f32_16x16x32_bf16 v[96:99], v[40:43], v[0:3], v[224:227]
	v_mfma_f32_16x16x32_bf16 v[164:167], v[40:43], v[8:11], v[228:231]
	s_waitcnt lgkmcnt(4)
	v_mfma_f32_16x16x32_bf16 v[96:99], v[44:47], v[4:7], v[96:99]
	v_mfma_f32_16x16x32_bf16 v[164:167], v[44:47], v[12:15], v[164:167]
	s_waitcnt lgkmcnt(0)
	v_fmamk_f32 v72, v72, 0x3e38aa3b, v36
	v_fmamk_f32 v73, v73, 0x3e38aa3b, v37
	v_fmamk_f32 v74, v74, 0x3e38aa3b, v38
	v_fmamk_f32 v75, v75, 0x3e38aa3b, v39
	v_fmamk_f32 v84, v84, 0x3e38aa3b, v36
	v_fmamk_f32 v85, v85, 0x3e38aa3b, v37
	v_fmamk_f32 v86, v86, 0x3e38aa3b, v38
	v_fmamk_f32 v87, v87, 0x3e38aa3b, v39
	v_fmamk_f32 v76, v76, 0x3e38aa3b, v32
	v_fmamk_f32 v77, v77, 0x3e38aa3b, v33
	v_fmamk_f32 v78, v78, 0x3e38aa3b, v34
	v_fmamk_f32 v79, v79, 0x3e38aa3b, v35
	v_fmamk_f32 v88, v88, 0x3e38aa3b, v32
	v_fmamk_f32 v89, v89, 0x3e38aa3b, v33
	v_fmamk_f32 v90, v90, 0x3e38aa3b, v34
	v_fmamk_f32 v91, v91, 0x3e38aa3b, v35
	v_fmamk_f32 v80, v80, 0x3e38aa3b, v28
	v_fmamk_f32 v81, v81, 0x3e38aa3b, v29
	v_fmamk_f32 v82, v82, 0x3e38aa3b, v30
	v_fmamk_f32 v83, v83, 0x3e38aa3b, v31
	v_fmamk_f32 v92, v92, 0x3e38aa3b, v28
	v_fmamk_f32 v93, v93, 0x3e38aa3b, v29
	v_fmamk_f32 v94, v94, 0x3e38aa3b, v30
	v_fmamk_f32 v95, v95, 0x3e38aa3b, v31
	v_fmamk_f32 v96, v96, 0x3e38aa3b, v24
	v_fmamk_f32 v97, v97, 0x3e38aa3b, v25
	v_fmamk_f32 v98, v98, 0x3e38aa3b, v26
	v_fmamk_f32 v99, v99, 0x3e38aa3b, v27
	v_fmamk_f32 v164, v164, 0x3e38aa3b, v24
	v_fmamk_f32 v165, v165, 0x3e38aa3b, v25
	v_fmamk_f32 v166, v166, 0x3e38aa3b, v26
	v_fmamk_f32 v167, v167, 0x3e38aa3b, v27
	v_max3_f32 v146, v72, v73, v74
	v_max3_f32 v147, v80, v81, v82
	v_max3_f32 v146, v146, v75, v84
	v_max3_f32 v147, v147, v83, v92
	v_max3_f32 v146, v146, v85, v86
	v_max3_f32 v147, v147, v93, v94
	v_max3_f32 v146, v146, v87, v76
	v_max3_f32 v147, v147, v95, v96
	v_max3_f32 v146, v146, v77, v78
	v_max3_f32 v147, v147, v97, v98
	v_max3_f32 v146, v146, v79, v88
	v_max3_f32 v147, v147, v99, v164
	v_max3_f32 v146, v146, v89, v90
	v_max3_f32 v147, v147, v165, v166
	v_max3_f32 v146, v146, v91, v91
	v_max3_f32 v147, v147, v167, v167
	v_max_f32_e32 v146, v146, v147
	v_cmp_lt_f32_e32 vcc, 0x42200000, v146
	s_cbranch_vccnz .Lfox1_slow
; DI unsigned pk2(float lo, float hi) { unsigned r; asm volatile("v_cvt_pk_bf16_f32 %0, %1, %2" : "=v"(r) : "v"(lo), "v"(hi)); return r; }
; DI float ex2(float x) { return __builtin_amdgcn_exp2f(x); }
; DI f32x4 mmaT(bf16x8 a_m, bf16x8 b_n, f32x4 c) { return __builtin_amdgcn_mfma_f32_16x16x32_bf16(b_n, a_m, c, 0, 0, 0); }
; template <bool DIAG>
; DI void fox_tile(const bf16_t* sK, const bf16_t* sV, const float* sFk, const bf16x8 (&qf)[2][2], f32x4 (&o)[2][4], float (&mrun)[2], float (&lsum)[2], int key0, int qg0, int fr, int fq, int lane) {
;     ...
;   bf16x8 vf[2][4];
; #pragma unroll
;   for (int k2 = 0; k2 < 2; ++k2)
; #pragma unroll
;     for (int d = 0; d < 4; ++d) {
;       const bf16_t* a = sV + (32 * k2 + 4 * fq + (fr >> 2)) * 72 + 16 * d + 4 * (fr & 3);
;       const v4i16_t lo = tr_rd(a), hi = tr_rd(a + 16 * 72);
;       vf[k2][d] = __builtin_shufflevector(lo, hi, 0, 1, 2, 3, 4, 5, 6, 7);
;     }
;   __builtin_amdgcn_sched_barrier(0);
; #pragma unroll
;   for (int mi = 0; mi < 2; ++mi) {
;     float mx = -INFINITY;
; #pragma unroll
;     for (int t = 0; t < 4; ++t)
; #pragma unroll
;       for (int j = 0; j < 4; ++j) {
;         float x = __builtin_fmaf(s[mi][t][j], SC2, fk[t][j]);
;         if (DIAG) { if (key0 + 16 * t + 4 * fq + j > qg0 + 16 * mi) x = -INFINITY; }
;         s[mi][t][j] = x; mx = fmaxf(mx, x);
;       }
;     mx = fmaxf(mx, shx(mx, 16, lane)); mx = fmaxf(mx, shx(mx, 32, lane));
;     const float mnew = fmaxf(mrun[mi], mx), alpha = ex2(mrun[mi] - mnew);
;     mrun[mi] = mnew;
;     float ps = 0.f;
; #pragma unroll
;     for (int t = 0; t < 4; ++t)
; #pragma unroll
;       for (int j = 0; j < 4; ++j) { const float pv = ex2(s[mi][t][j] - mnew); s[mi][t][j] = pv; ps += pv; }
;     lsum[mi] = lsum[mi] * alpha + ps;
; #pragma unroll
;     for (int d = 0; d < 4; ++d) o[mi][d] *= alpha;
;   }
; #pragma unroll
;   for (int k2 = 0; k2 < 2; ++k2) {
;     bf16x8 pa[2];
; #pragma unroll
;     for (int mi = 0; mi < 2; ++mi) pa[mi] = mk8(pk2(s[mi][2 * k2][0], s[mi][2 * k2][1]), pk2(s[mi][2 * k2][2], s[mi][2 * k2][3]), pk2(s[mi][2 * k2 + 1][0], s[mi][2 * k2 + 1][1]), pk2(s[mi][2 * k2 + 1][2], s[mi][2 * k2 + 1][3]));
; #pragma unroll
;     for (int d = 0; d < 4; ++d) {
; #pragma unroll
;       for (int mi = 0; mi < 2; ++mi) o[mi][d] = mmaT(pa[mi], vf[k2][d], o[mi][d]);
;     }
	ds_read_b64_tr_b16 v[68:69], v221 offset:9216
	ds_read_b64_tr_b16 v[60:61], v221 offset:9248
	ds_read_b64_tr_b16 v[64:65], v221 offset:9280
	ds_read_b64_tr_b16 v[56:57], v221 offset:9312
	ds_read_b64_tr_b16 v[70:71], v221 offset:11520
	ds_read_b64_tr_b16 v[62:63], v221 offset:11552
	ds_read_b64_tr_b16 v[66:67], v221 offset:11584
	ds_read_b64_tr_b16 v[58:59], v221 offset:11616
	ds_read_b64_tr_b16 v[52:53], v221 offset:13824
	ds_read_b64_tr_b16 v[48:49], v221 offset:13856
	ds_read_b64_tr_b16 v[44:45], v221 offset:13888
	ds_read_b64_tr_b16 v[40:41], v221 offset:13920
	ds_read_b64_tr_b16 v[54:55], v221 offset:16128
	ds_read_b64_tr_b16 v[50:51], v221 offset:16160
	ds_read_b64_tr_b16 v[46:47], v221 offset:16192
	ds_read_b64_tr_b16 v[42:43], v221 offset:16224
	v_exp_f32_e32 v72, v72
	v_exp_f32_e32 v73, v73
	v_exp_f32_e32 v74, v74
	v_exp_f32_e32 v75, v75
	v_exp_f32_e32 v76, v76
	v_exp_f32_e32 v77, v77
	v_exp_f32_e32 v78, v78
	v_exp_f32_e32 v79, v79
	v_exp_f32_e32 v80, v80
	v_exp_f32_e32 v81, v81
	v_exp_f32_e32 v82, v82
	v_exp_f32_e32 v83, v83
	v_exp_f32_e32 v96, v96
	v_exp_f32_e32 v97, v97
	v_exp_f32_e32 v98, v98
	v_exp_f32_e32 v99, v99
	v_add_f32_e32 v146, v72, v73
	v_add_f32_e32 v147, v74, v75
	v_add_f32_e32 v148, v76, v77
	v_add_f32_e32 v149, v78, v79
	v_add_f32_e32 v150, v80, v81
	v_add_f32_e32 v151, v82, v83
	v_add_f32_e32 v152, v96, v97
	v_add_f32_e32 v153, v98, v99
	v_add_f32_e32 v146, v146, v147
	v_add_f32_e32 v147, v148, v149
	v_add_f32_e32 v148, v150, v151
	v_add_f32_e32 v149, v152, v153
	v_add_f32_e32 v146, v146, v147
	v_add_f32_e32 v148, v148, v149
	v_add_f32_e32 v146, v146, v148
	v_add_f32_e32 v128, v128, v146
	v_cvt_pk_bf16_f32 v36, v72, v73
	v_cvt_pk_bf16_f32 v37, v74, v75
	v_cvt_pk_bf16_f32 v38, v76, v77
	v_cvt_pk_bf16_f32 v39, v78, v79
	v_cvt_pk_bf16_f32 v28, v80, v81
	v_cvt_pk_bf16_f32 v29, v82, v83
	v_cvt_pk_bf16_f32 v30, v96, v97
	v_cvt_pk_bf16_f32 v31, v98, v99
	s_waitcnt lgkmcnt(8)
	v_mfma_f32_16x16x32_bf16 v[142:145], v[68:71], v[36:39], v[142:145]
	v_exp_f32_e32 v84, v84
	v_exp_f32_e32 v85, v85
	v_mfma_f32_16x16x32_bf16 v[138:141], v[60:63], v[36:39], v[138:141]
	v_exp_f32_e32 v86, v86
	v_exp_f32_e32 v87, v87
	v_mfma_f32_16x16x32_bf16 v[134:137], v[64:67], v[36:39], v[134:137]
	v_exp_f32_e32 v88, v88
	v_exp_f32_e32 v89, v89
	v_mfma_f32_16x16x32_bf16 v[130:133], v[56:59], v[36:39], v[130:133]
	v_exp_f32_e32 v90, v90
	v_exp_f32_e32 v91, v91
	s_waitcnt lgkmcnt(0)
	v_mfma_f32_16x16x32_bf16 v[142:145], v[52:55], v[28:31], v[142:145]
	v_exp_f32_e32 v92, v92
	v_exp_f32_e32 v93, v93
	v_mfma_f32_16x16x32_bf16 v[138:141], v[48:51], v[28:31], v[138:141]
	v_exp_f32_e32 v94, v94
	v_exp_f32_e32 v95, v95
	v_mfma_f32_16x16x32_bf16 v[134:137], v[44:47], v[28:31], v[134:137]
	v_exp_f32_e32 v164, v164
	v_exp_f32_e32 v165, v165
	v_mfma_f32_16x16x32_bf16 v[130:133], v[40:43], v[28:31], v[130:133]
	v_exp_f32_e32 v166, v166
	v_exp_f32_e32 v167, v167
	v_add_f32_e32 v146, v84, v85
	v_add_f32_e32 v147, v86, v87
	v_add_f32_e32 v148, v88, v89
	v_add_f32_e32 v149, v90, v91
	v_add_f32_e32 v150, v92, v93
	v_add_f32_e32 v151, v94, v95
	v_add_f32_e32 v152, v164, v165
	v_add_f32_e32 v153, v166, v167
	v_add_f32_e32 v146, v146, v147
	v_add_f32_e32 v147, v148, v149
	v_add_f32_e32 v148, v150, v151
	v_add_f32_e32 v149, v152, v153
	v_add_f32_e32 v146, v146, v147
	v_add_f32_e32 v148, v148, v149
	v_add_f32_e32 v146, v146, v148
	v_add_f32_e32 v129, v129, v146
	v_cvt_pk_bf16_f32 v32, v84, v85
	v_cvt_pk_bf16_f32 v33, v86, v87
	v_cvt_pk_bf16_f32 v34, v88, v89
	v_cvt_pk_bf16_f32 v35, v90, v91
	v_cvt_pk_bf16_f32 v24, v92, v93
	v_cvt_pk_bf16_f32 v25, v94, v95
	v_cvt_pk_bf16_f32 v26, v164, v165
	v_cvt_pk_bf16_f32 v27, v166, v167
	s_nop 1
	v_mfma_f32_16x16x32_bf16 v[122:125], v[68:71], v[32:35], v[122:125]
	v_mfma_f32_16x16x32_bf16 v[118:121], v[60:63], v[32:35], v[118:121]
	v_mfma_f32_16x16x32_bf16 v[114:117], v[64:67], v[32:35], v[114:117]
	v_mfma_f32_16x16x32_bf16 v[110:113], v[56:59], v[32:35], v[110:113]
	v_mfma_f32_16x16x32_bf16 v[122:125], v[52:55], v[24:27], v[122:125]
	v_mfma_f32_16x16x32_bf16 v[118:121], v[48:51], v[24:27], v[118:121]
	v_mfma_f32_16x16x32_bf16 v[114:117], v[44:47], v[24:27], v[114:117]
	v_mfma_f32_16x16x32_bf16 v[110:113], v[40:43], v[24:27], v[110:113]
	s_branch .Lfox1_join
